# v34 + GEMM units: first K-tile pair peeled with C = 0 on each accumulator's first MFMA, the 128-instruction accumulator zeroing pass per unit removed
# speedup vs baseline: 1.0106x; 1.0106x over previous
; #define PG8_STAGE(bufoff, gbase, voff) do { _Pragma("unroll") for (int _i = 0; _i < 2; ++_i) \
;         __builtin_amdgcn_global_load_lds((const unsigned*)((const char*)(gbase) + (voff)[_i]), (PG8_LAS unsigned*)(lds + (bufoff) + ldsw + _i * 8192), 16, 0, 0); } while (0)
; #define PG8_LDA(dst, b, h) do { _Pragma("unroll") for (int m = 0; m < 4; ++m) _Pragma("unroll") for (int k = 0; k < 2; ++k) dst[m][k] = *(const PG8_LAS bf16x8*)(lds + PG8_SA(b, h) + aoff + m * 2048 + k * 1024); } while (0)
; #define PG8_LDB(dst, b, h) do { _Pragma("unroll") for (int n = 0; n < 2; ++n) _Pragma("unroll") for (int k = 0; k < 2; ++k) dst[n][k] = *(const PG8_LAS bf16x8*)(lds + PG8_SB(b, h) + boff + n * 2048 + k * 1024); } while (0)
; #define PG8_WAIT_V(n) asm volatile("s_waitcnt vmcnt(" #n ")" ::: "memory")
; #define PG8_WAIT_L(n) asm volatile("s_waitcnt lgkmcnt(" #n ")" ::: "memory")
; #define PG8_BAR __builtin_amdgcn_s_barrier()
; #define PG8_SCHED __builtin_amdgcn_sched_barrier(0)
; template <class Epi, class Sched, bool ALIGN_EPI = false, bool SP2 = false>
; __device__ __forceinline__ void gemm_phase(PG8_LAS unsigned char* lds, const Gemm g, const Sched& S, const Epi& E) {
;     ...
;     for (;;) {
;         const bool has_next = S.next(ui + 1, nxt);
;         const char* nA = has_next ? (const char*)g.A + (size_t)nxt.pm * tstep : cA; const char* nB = has_next ? (const char*)g.Bt + (size_t)nxt.pn * tstep : cB;
;         for (int t = 0; t < nt; t += 2) {
;             const bool last = (t == nt - 2);
;             const char* a1 = cA + (size_t)(t + 1) * kstep;
;             const char* a2 = last ? nA : cA + (size_t)(t + 2) * kstep; const char* b2 = last ? nB : cB + (size_t)(t + 2) * kstep;
;             const char* a3 = a2 + kstep; const char* b3 = b2 + kstep;
;             if (last && has_next) S.a_ready(nxt);
;             if constexpr (SP2) {
;             PG8_LDB(B0, 0, 0); PG8_LDB(B1, 0, 1); PG8_SCHED; PG8_LDA(At, 0, 0); PG8_STAGE(PG8_SA(1, 1), a1 + hstep, voffA);
;             PG8_WAIT_V(8); PG8_WAIT_L(0); PG8_BAR; PG8_MMA(0, 0, At, B0); PG8_MMA(0, 1, At, B1); PG8_BAR; PG8_SCHED;
;             PG8_LDA(At, 0, 1); PG8_STAGE(PG8_SB(0, 0), b2, voffB); PG8_STAGE(PG8_SB(0, 1), b2 + hstep, voffB); PG8_STAGE(PG8_SA(0, 0), a2, voffA);
;             PG8_WAIT_V(8); PG8_WAIT_L(0); PG8_BAR; PG8_MMA(1, 0, At, B0); PG8_MMA(1, 1, At, B1); PG8_BAR; PG8_SCHED;
.LBB0_306:
	s_add_u32 s10, s2, 0x100
	s_addc_u32 s11, s3, 0
	s_add_u32 s2, s8, 0x80
	s_addc_u32 s3, s9, 0
	s_mov_b32 s8, 0
	s_add_i32 s26, s8, 2
	s_add_u32 s27, s2, 0x80
	s_addc_u32 s9, s3, 0
	s_add_i32 s30, 0, 0x10000
	s_cmp_eq_u32 s54, s8
	s_cselect_b32 s9, s1, s9
	s_cselect_b32 s8, s0, s27
	s_cselect_b32 s29, s25, s11
	s_cselect_b32 s28, s24, s10
	s_add_i32 s27, 0, 0x14000
	v_add_u32_e32 v140, s30, v179
	v_add_u32_e32 v156, s27, v179
	ds_read_b128 v[128:131], v140
	ds_read_b128 v[132:135], v140 offset:1024
	ds_read_b128 v[136:139], v140 offset:2048
	ds_read_b128 v[140:143], v140 offset:3072
	ds_read_b128 v[144:147], v156
	ds_read_b128 v[148:151], v156 offset:1024
	ds_read_b128 v[152:155], v156 offset:2048
	ds_read_b128 v[156:159], v156 offset:3072
	v_lshl_add_u64 v[208:209], s[2:3], 0, v[170:171]
	s_add_i32 m0, s47, 0xc000
	ds_read_b128 v[172:175], v228
	ds_read_b128 v[180:183], v228 offset:1024
	ds_read_b128 v[184:187], v228 offset:2048
	ds_read_b128 v[188:191], v228 offset:3072
	ds_read_b128 v[192:195], v228 offset:4096
	ds_read_b128 v[196:199], v228 offset:5120
	ds_read_b128 v[200:203], v228 offset:6144
	ds_read_b128 v[204:207], v228 offset:7168
	global_load_lds_dwordx4 v[208:209], off
	v_lshl_add_u64 v[208:209], s[2:3], 0, v[168:169]
	s_add_i32 m0, s47, 0xe000
	s_nop 0
	global_load_lds_dwordx4 v[208:209], off
	s_waitcnt vmcnt(8)
	s_waitcnt lgkmcnt(0)
	s_barrier
	s_waitcnt lgkmcnt(0)
	v_mfma_f32_16x16x32_bf16 v[124:127], v[128:131], v[172:175], 0
	v_mfma_f32_16x16x32_bf16 v[120:123], v[136:139], v[172:175], 0
	v_mfma_f32_16x16x32_bf16 v[108:111], v[128:131], v[184:187], 0
	v_mfma_f32_16x16x32_bf16 v[104:107], v[136:139], v[184:187], 0
	v_mfma_f32_16x16x32_bf16 v[92:95], v[128:131], v[192:195], 0
	v_mfma_f32_16x16x32_bf16 v[88:91], v[136:139], v[192:195], 0
	v_mfma_f32_16x16x32_bf16 v[76:79], v[128:131], v[200:203], 0
	v_mfma_f32_16x16x32_bf16 v[72:75], v[136:139], v[200:203], 0
	v_mfma_f32_16x16x32_bf16 v[124:127], v[132:135], v[180:183], v[124:127]
	v_mfma_f32_16x16x32_bf16 v[120:123], v[140:143], v[180:183], v[120:123]
	v_mfma_f32_16x16x32_bf16 v[108:111], v[132:135], v[188:191], v[108:111]
	v_mfma_f32_16x16x32_bf16 v[104:107], v[140:143], v[188:191], v[104:107]
	v_mfma_f32_16x16x32_bf16 v[92:95], v[132:135], v[196:199], v[92:95]
	v_mfma_f32_16x16x32_bf16 v[88:91], v[140:143], v[196:199], v[88:91]
	v_mfma_f32_16x16x32_bf16 v[76:79], v[132:135], v[204:207], v[76:79]
	v_mfma_f32_16x16x32_bf16 v[72:75], v[140:143], v[204:207], v[72:75]
	v_mfma_f32_16x16x32_bf16 v[116:119], v[144:147], v[172:175], 0
	v_mfma_f32_16x16x32_bf16 v[112:115], v[152:155], v[172:175], 0
	v_mfma_f32_16x16x32_bf16 v[100:103], v[144:147], v[184:187], 0
	v_mfma_f32_16x16x32_bf16 v[96:99], v[152:155], v[184:187], 0
	v_mfma_f32_16x16x32_bf16 v[84:87], v[144:147], v[192:195], 0
	v_mfma_f32_16x16x32_bf16 v[80:83], v[152:155], v[192:195], 0
	v_mfma_f32_16x16x32_bf16 v[68:71], v[144:147], v[200:203], 0
	v_mfma_f32_16x16x32_bf16 v[64:67], v[152:155], v[200:203], 0
	v_mfma_f32_16x16x32_bf16 v[116:119], v[148:151], v[180:183], v[116:119]
	v_mfma_f32_16x16x32_bf16 v[112:115], v[156:159], v[180:183], v[112:115]
	v_mfma_f32_16x16x32_bf16 v[100:103], v[148:151], v[188:191], v[100:103]
	v_mfma_f32_16x16x32_bf16 v[96:99], v[156:159], v[188:191], v[96:99]
	v_mfma_f32_16x16x32_bf16 v[84:87], v[148:151], v[196:199], v[84:87]
	v_mfma_f32_16x16x32_bf16 v[80:83], v[156:159], v[196:199], v[80:83]
	v_mfma_f32_16x16x32_bf16 v[68:71], v[148:151], v[204:207], v[68:71]
	v_mfma_f32_16x16x32_bf16 v[64:67], v[156:159], v[204:207], v[64:67]
	s_barrier
	s_add_i32 s30, s30, s46
	v_lshl_add_u64 v[208:209], s[28:29], 0, v[162:163]
	s_mov_b32 m0, s30
	ds_read_b128 v[172:175], v228 offset:16384
	ds_read_b128 v[180:183], v228 offset:17408
	ds_read_b128 v[184:187], v228 offset:18432
	ds_read_b128 v[188:191], v228 offset:19456
	ds_read_b128 v[192:195], v228 offset:20480
	ds_read_b128 v[196:199], v228 offset:21504
	ds_read_b128 v[200:203], v228 offset:22528
	ds_read_b128 v[204:207], v228 offset:23552
	global_load_lds_dwordx4 v[208:209], off
	s_add_i32 m0, s30, 0x2000
	v_lshl_add_u64 v[210:211], s[28:29], 0, v[166:167]
	s_add_u32 s28, s28, s88
	s_addc_u32 s29, s29, 0
	s_add_i32 s27, s27, s46
	global_load_lds_dwordx4 v[210:211], off
	v_lshl_add_u64 v[212:213], s[28:29], 0, v[162:163]
	s_mov_b32 m0, s27
	v_lshl_add_u64 v[214:215], s[28:29], 0, v[166:167]
	global_load_lds_dwordx4 v[212:213], off
	s_add_i32 m0, s27, 0x2000
	v_lshl_add_u64 v[230:231], s[8:9], 0, v[160:161]
	global_load_lds_dwordx4 v[214:215], off
	s_mov_b32 m0, s47
	v_lshl_add_u64 v[232:233], s[8:9], 0, v[164:165]
	global_load_lds_dwordx4 v[230:231], off
	s_mov_b32 m0, s48
	s_nop 0
	global_load_lds_dwordx4 v[232:233], off
	s_waitcnt vmcnt(8)
	s_waitcnt lgkmcnt(0)
	s_barrier
; #define PG8_STAGE(bufoff, gbase, voff) do { _Pragma("unroll") for (int _i = 0; _i < 2; ++_i) \
;         __builtin_amdgcn_global_load_lds((const unsigned*)((const char*)(gbase) + (voff)[_i]), (PG8_LAS unsigned*)(lds + (bufoff) + ldsw + _i * 8192), 16, 0, 0); } while (0)
; #define PG8_LDA(dst, b, h) do { _Pragma("unroll") for (int m = 0; m < 4; ++m) _Pragma("unroll") for (int k = 0; k < 2; ++k) dst[m][k] = *(const PG8_LAS bf16x8*)(lds + PG8_SA(b, h) + aoff + m * 2048 + k * 1024); } while (0)
; #define PG8_LDB(dst, b, h) do { _Pragma("unroll") for (int n = 0; n < 2; ++n) _Pragma("unroll") for (int k = 0; k < 2; ++k) dst[n][k] = *(const PG8_LAS bf16x8*)(lds + PG8_SB(b, h) + boff + n * 2048 + k * 1024); } while (0)
; #define PG8_MMA(ai, bj, At, Bt) do { __builtin_amdgcn_s_setprio(1); _Pragma("unroll") for (int m = 0; m < 4; ++m) _Pragma("unroll") for (int n = 0; n < 2; ++n) _Pragma("unroll") for (int k = 0; k < 2; ++k) \
;         acc[ai][bj][m][n] = __builtin_amdgcn_mfma_f32_16x16x32_bf16(Bt[n][k], At[m][k], acc[ai][bj][m][n], 0, 0, 0); __builtin_amdgcn_s_setprio(0); } while (0)
; #define PG8_WAIT_V(n) asm volatile("s_waitcnt vmcnt(" #n ")" ::: "memory")
; template <class Epi, class Sched, bool ALIGN_EPI = false, bool SP2 = false>
; __device__ __forceinline__ void gemm_phase(PG8_LAS unsigned char* lds, const Gemm g, const Sched& S, const Epi& E) {
;     ...
;             PG8_LDB(B0, 0, 0); PG8_LDB(B1, 0, 1); PG8_SCHED; PG8_LDA(At, 0, 0); PG8_STAGE(PG8_SA(1, 1), a1 + hstep, voffA);
;             PG8_WAIT_V(8); PG8_WAIT_L(0); PG8_BAR; PG8_MMA(0, 0, At, B0); PG8_MMA(0, 1, At, B1); PG8_BAR; PG8_SCHED;
;             PG8_LDA(At, 0, 1); PG8_STAGE(PG8_SB(0, 0), b2, voffB); PG8_STAGE(PG8_SB(0, 1), b2 + hstep, voffB); PG8_STAGE(PG8_SA(0, 0), a2, voffA);
;             PG8_WAIT_V(8); PG8_WAIT_L(0); PG8_BAR; PG8_MMA(1, 0, At, B0); PG8_MMA(1, 1, At, B1); PG8_BAR; PG8_SCHED;
;             PG8_LDB(B0, 1, 0); PG8_LDB(B1, 1, 1); PG8_SCHED; PG8_LDA(At, 1, 0); PG8_STAGE(PG8_SA(0, 1), a2 + hstep, voffA);
;             PG8_WAIT_V(8); PG8_WAIT_L(0); PG8_BAR; PG8_MMA(0, 0, At, B0); PG8_MMA(0, 1, At, B1); PG8_BAR; PG8_SCHED;
;             PG8_LDA(At, 1, 1); PG8_STAGE(PG8_SB(1, 0), b3, voffB); PG8_STAGE(PG8_SB(1, 1), b3 + hstep, voffB); PG8_STAGE(PG8_SA(1, 0), a3, voffA);
;             PG8_WAIT_V(8); PG8_WAIT_L(0); PG8_BAR; PG8_MMA(1, 0, At, B0); PG8_MMA(1, 1, At, B1); PG8_BAR; PG8_SCHED;
	s_waitcnt lgkmcnt(0)
	v_mfma_f32_16x16x32_bf16 v[60:63], v[128:131], v[172:175], 0
	v_mfma_f32_16x16x32_bf16 v[56:59], v[136:139], v[172:175], 0
	v_mfma_f32_16x16x32_bf16 v[44:47], v[128:131], v[184:187], 0
	v_mfma_f32_16x16x32_bf16 v[40:43], v[136:139], v[184:187], 0
	v_mfma_f32_16x16x32_bf16 v[28:31], v[128:131], v[192:195], 0
	v_mfma_f32_16x16x32_bf16 v[24:27], v[136:139], v[192:195], 0
	v_mfma_f32_16x16x32_bf16 v[12:15], v[128:131], v[200:203], 0
	v_mfma_f32_16x16x32_bf16 v[8:11], v[136:139], v[200:203], 0
	v_mfma_f32_16x16x32_bf16 v[60:63], v[132:135], v[180:183], v[60:63]
	v_mfma_f32_16x16x32_bf16 v[56:59], v[140:143], v[180:183], v[56:59]
	v_mfma_f32_16x16x32_bf16 v[44:47], v[132:135], v[188:191], v[44:47]
	v_mfma_f32_16x16x32_bf16 v[40:43], v[140:143], v[188:191], v[40:43]
	v_mfma_f32_16x16x32_bf16 v[28:31], v[132:135], v[196:199], v[28:31]
	v_mfma_f32_16x16x32_bf16 v[24:27], v[140:143], v[196:199], v[24:27]
	v_mfma_f32_16x16x32_bf16 v[12:15], v[132:135], v[204:207], v[12:15]
	v_mfma_f32_16x16x32_bf16 v[8:11], v[140:143], v[204:207], v[8:11]
	v_mfma_f32_16x16x32_bf16 v[52:55], v[144:147], v[172:175], 0
	v_mfma_f32_16x16x32_bf16 v[48:51], v[152:155], v[172:175], 0
	v_mfma_f32_16x16x32_bf16 v[36:39], v[144:147], v[184:187], 0
	v_mfma_f32_16x16x32_bf16 v[32:35], v[152:155], v[184:187], 0
	v_mfma_f32_16x16x32_bf16 v[20:23], v[144:147], v[192:195], 0
	v_mfma_f32_16x16x32_bf16 v[16:19], v[152:155], v[192:195], 0
	v_mfma_f32_16x16x32_bf16 v[4:7], v[144:147], v[200:203], 0
	v_mfma_f32_16x16x32_bf16 v[0:3], v[152:155], v[200:203], 0
	v_mfma_f32_16x16x32_bf16 v[52:55], v[148:151], v[180:183], v[52:55]
	v_mfma_f32_16x16x32_bf16 v[48:51], v[156:159], v[180:183], v[48:51]
	v_mfma_f32_16x16x32_bf16 v[36:39], v[148:151], v[188:191], v[36:39]
	v_mfma_f32_16x16x32_bf16 v[32:35], v[156:159], v[188:191], v[32:35]
	v_mfma_f32_16x16x32_bf16 v[20:23], v[148:151], v[196:199], v[20:23]
	v_mfma_f32_16x16x32_bf16 v[16:19], v[156:159], v[196:199], v[16:19]
	v_mfma_f32_16x16x32_bf16 v[4:7], v[148:151], v[204:207], v[4:7]
	v_mfma_f32_16x16x32_bf16 v[0:3], v[156:159], v[204:207], v[0:3]
	s_barrier
	s_add_i32 s27, 0, 0x18000
	s_add_i32 s28, 0, 0x1c000
	v_add_u32_e32 v140, s27, v179
	v_add_u32_e32 v156, s28, v179
	ds_read_b128 v[128:131], v140
	ds_read_b128 v[132:135], v140 offset:1024
	ds_read_b128 v[136:139], v140 offset:2048
	ds_read_b128 v[140:143], v140 offset:3072
	ds_read_b128 v[144:147], v156
	ds_read_b128 v[148:151], v156 offset:1024
	ds_read_b128 v[152:155], v156 offset:2048
	ds_read_b128 v[156:159], v156 offset:3072
	s_add_u32 s8, s8, s88
	s_addc_u32 s9, s9, 0
	s_mov_b32 m0, s49
	v_lshl_add_u64 v[234:235], s[8:9], 0, v[160:161]
	ds_read_b128 v[172:175], v228 offset:32768
	ds_read_b128 v[180:183], v228 offset:33792
	ds_read_b128 v[184:187], v228 offset:34816
	ds_read_b128 v[188:191], v228 offset:35840
	ds_read_b128 v[192:195], v228 offset:36864
	ds_read_b128 v[196:199], v228 offset:37888
	ds_read_b128 v[200:203], v228 offset:38912
	ds_read_b128 v[204:207], v228 offset:39936
	global_load_lds_dwordx4 v[234:235], off
	v_lshl_add_u64 v[234:235], s[8:9], 0, v[164:165]
	s_mov_b32 m0, s50
	s_nop 0
	global_load_lds_dwordx4 v[234:235], off
	s_waitcnt vmcnt(8)
	s_waitcnt lgkmcnt(0)
	s_barrier
	s_waitcnt lgkmcnt(0)
	v_mfma_f32_16x16x32_bf16 v[124:127], v[128:131], v[172:175], v[124:127]
	v_mfma_f32_16x16x32_bf16 v[120:123], v[136:139], v[172:175], v[120:123]
	v_mfma_f32_16x16x32_bf16 v[108:111], v[128:131], v[184:187], v[108:111]
	v_mfma_f32_16x16x32_bf16 v[104:107], v[136:139], v[184:187], v[104:107]
	v_mfma_f32_16x16x32_bf16 v[92:95], v[128:131], v[192:195], v[92:95]
	v_mfma_f32_16x16x32_bf16 v[88:91], v[136:139], v[192:195], v[88:91]
	v_mfma_f32_16x16x32_bf16 v[76:79], v[128:131], v[200:203], v[76:79]
	v_mfma_f32_16x16x32_bf16 v[72:75], v[136:139], v[200:203], v[72:75]
	v_mfma_f32_16x16x32_bf16 v[124:127], v[132:135], v[180:183], v[124:127]
	v_mfma_f32_16x16x32_bf16 v[120:123], v[140:143], v[180:183], v[120:123]
	v_mfma_f32_16x16x32_bf16 v[108:111], v[132:135], v[188:191], v[108:111]
	v_mfma_f32_16x16x32_bf16 v[104:107], v[140:143], v[188:191], v[104:107]
	v_mfma_f32_16x16x32_bf16 v[92:95], v[132:135], v[196:199], v[92:95]
	v_mfma_f32_16x16x32_bf16 v[88:91], v[140:143], v[196:199], v[88:91]
	v_mfma_f32_16x16x32_bf16 v[76:79], v[132:135], v[204:207], v[76:79]
	v_mfma_f32_16x16x32_bf16 v[72:75], v[140:143], v[204:207], v[72:75]
	v_mfma_f32_16x16x32_bf16 v[116:119], v[144:147], v[172:175], v[116:119]
	v_mfma_f32_16x16x32_bf16 v[112:115], v[152:155], v[172:175], v[112:115]
	v_mfma_f32_16x16x32_bf16 v[100:103], v[144:147], v[184:187], v[100:103]
	v_mfma_f32_16x16x32_bf16 v[96:99], v[152:155], v[184:187], v[96:99]
	v_mfma_f32_16x16x32_bf16 v[84:87], v[144:147], v[192:195], v[84:87]
	v_mfma_f32_16x16x32_bf16 v[80:83], v[152:155], v[192:195], v[80:83]
	v_mfma_f32_16x16x32_bf16 v[68:71], v[144:147], v[200:203], v[68:71]
	v_mfma_f32_16x16x32_bf16 v[64:67], v[152:155], v[200:203], v[64:67]
	v_mfma_f32_16x16x32_bf16 v[116:119], v[148:151], v[180:183], v[116:119]
	v_mfma_f32_16x16x32_bf16 v[112:115], v[156:159], v[180:183], v[112:115]
	v_mfma_f32_16x16x32_bf16 v[100:103], v[148:151], v[188:191], v[100:103]
	v_mfma_f32_16x16x32_bf16 v[96:99], v[156:159], v[188:191], v[96:99]
	v_mfma_f32_16x16x32_bf16 v[84:87], v[148:151], v[196:199], v[84:87]
	v_mfma_f32_16x16x32_bf16 v[80:83], v[156:159], v[196:199], v[80:83]
	v_mfma_f32_16x16x32_bf16 v[68:71], v[148:151], v[204:207], v[68:71]
	v_mfma_f32_16x16x32_bf16 v[64:67], v[156:159], v[204:207], v[64:67]
	s_barrier
; #define PG8_STAGE(bufoff, gbase, voff) do { _Pragma("unroll") for (int _i = 0; _i < 2; ++_i) \
;         __builtin_amdgcn_global_load_lds((const unsigned*)((const char*)(gbase) + (voff)[_i]), (PG8_LAS unsigned*)(lds + (bufoff) + ldsw + _i * 8192), 16, 0, 0); } while (0)
; #define PG8_LDA(dst, b, h) do { _Pragma("unroll") for (int m = 0; m < 4; ++m) _Pragma("unroll") for (int k = 0; k < 2; ++k) dst[m][k] = *(const PG8_LAS bf16x8*)(lds + PG8_SA(b, h) + aoff + m * 2048 + k * 1024); } while (0)
; #define PG8_LDB(dst, b, h) do { _Pragma("unroll") for (int n = 0; n < 2; ++n) _Pragma("unroll") for (int k = 0; k < 2; ++k) dst[n][k] = *(const PG8_LAS bf16x8*)(lds + PG8_SB(b, h) + boff + n * 2048 + k * 1024); } while (0)
; #define PG8_MMA(ai, bj, At, Bt) do { __builtin_amdgcn_s_setprio(1); _Pragma("unroll") for (int m = 0; m < 4; ++m) _Pragma("unroll") for (int n = 0; n < 2; ++n) _Pragma("unroll") for (int k = 0; k < 2; ++k) \
;         acc[ai][bj][m][n] = __builtin_amdgcn_mfma_f32_16x16x32_bf16(Bt[n][k], At[m][k], acc[ai][bj][m][n], 0, 0, 0); __builtin_amdgcn_s_setprio(0); } while (0)
; #define PG8_WAIT_V(n) asm volatile("s_waitcnt vmcnt(" #n ")" ::: "memory")
; #define PG8_WAIT_L(n) asm volatile("s_waitcnt lgkmcnt(" #n ")" ::: "memory")
; #define PG8_BAR __builtin_amdgcn_s_barrier()
; #define PG8_SCHED __builtin_amdgcn_sched_barrier(0)
; template <class Epi, class Sched, bool ALIGN_EPI = false, bool SP2 = false>
; __device__ __forceinline__ void gemm_phase(PG8_LAS unsigned char* lds, const Gemm g, const Sched& S, const Epi& E) {
;     ...
;             PG8_LDB(B0, 1, 0); PG8_LDB(B1, 1, 1); PG8_SCHED; PG8_LDA(At, 1, 0); PG8_STAGE(PG8_SA(0, 1), a2 + hstep, voffA);
;             PG8_WAIT_V(8); PG8_WAIT_L(0); PG8_BAR; PG8_MMA(0, 0, At, B0); PG8_MMA(0, 1, At, B1); PG8_BAR; PG8_SCHED;
;             PG8_LDA(At, 1, 1); PG8_STAGE(PG8_SB(1, 0), b3, voffB); PG8_STAGE(PG8_SB(1, 1), b3 + hstep, voffB); PG8_STAGE(PG8_SA(1, 0), a3, voffA);
;             PG8_WAIT_V(8); PG8_WAIT_L(0); PG8_BAR; PG8_MMA(1, 0, At, B0); PG8_MMA(1, 1, At, B1); PG8_BAR; PG8_SCHED;
	s_add_i32 s8, s27, s46
	v_lshl_add_u64 v[208:209], v[208:209], 0, s[94:95]
	s_mov_b32 m0, s8
	ds_read_b128 v[172:175], v228 offset:49152
	ds_read_b128 v[180:183], v228 offset:50176
	ds_read_b128 v[184:187], v228 offset:51200
	ds_read_b128 v[188:191], v228 offset:52224
	ds_read_b128 v[192:195], v228 offset:53248
	ds_read_b128 v[196:199], v228 offset:54272
	ds_read_b128 v[200:203], v228 offset:55296
	ds_read_b128 v[204:207], v228 offset:56320
	global_load_lds_dwordx4 v[208:209], off
	v_lshl_add_u64 v[208:209], v[210:211], 0, s[94:95]
	s_add_i32 m0, s8, 0x2000
	s_add_i32 s8, s28, s46
	global_load_lds_dwordx4 v[208:209], off
	v_lshl_add_u64 v[208:209], v[212:213], 0, s[94:95]
	s_mov_b32 m0, s8
	s_nop 0
	global_load_lds_dwordx4 v[208:209], off
	v_lshl_add_u64 v[208:209], v[214:215], 0, s[94:95]
	s_add_i32 m0, s8, 0x2000
	s_nop 0
	global_load_lds_dwordx4 v[208:209], off
	v_lshl_add_u64 v[208:209], v[230:231], 0, s[94:95]
	s_mov_b32 m0, s52
	s_nop 0
	global_load_lds_dwordx4 v[208:209], off
	v_lshl_add_u64 v[208:209], v[232:233], 0, s[94:95]
	s_mov_b32 m0, s53
	s_nop 0
	global_load_lds_dwordx4 v[208:209], off
	s_waitcnt vmcnt(8)
	s_waitcnt lgkmcnt(0)
	s_barrier
	s_waitcnt lgkmcnt(0)
	v_mfma_f32_16x16x32_bf16 v[60:63], v[128:131], v[172:175], v[60:63]
	v_mfma_f32_16x16x32_bf16 v[56:59], v[136:139], v[172:175], v[56:59]
	v_mfma_f32_16x16x32_bf16 v[44:47], v[128:131], v[184:187], v[44:47]
	v_mfma_f32_16x16x32_bf16 v[40:43], v[136:139], v[184:187], v[40:43]
	v_mfma_f32_16x16x32_bf16 v[28:31], v[128:131], v[192:195], v[28:31]
	v_mfma_f32_16x16x32_bf16 v[24:27], v[136:139], v[192:195], v[24:27]
	v_mfma_f32_16x16x32_bf16 v[12:15], v[128:131], v[200:203], v[12:15]
	v_mfma_f32_16x16x32_bf16 v[8:11], v[136:139], v[200:203], v[8:11]
	v_mfma_f32_16x16x32_bf16 v[60:63], v[132:135], v[180:183], v[60:63]
	v_mfma_f32_16x16x32_bf16 v[56:59], v[140:143], v[180:183], v[56:59]
	v_mfma_f32_16x16x32_bf16 v[44:47], v[132:135], v[188:191], v[44:47]
	v_mfma_f32_16x16x32_bf16 v[40:43], v[140:143], v[188:191], v[40:43]
	v_mfma_f32_16x16x32_bf16 v[28:31], v[132:135], v[196:199], v[28:31]
	v_mfma_f32_16x16x32_bf16 v[24:27], v[140:143], v[196:199], v[24:27]
	v_mfma_f32_16x16x32_bf16 v[12:15], v[132:135], v[204:207], v[12:15]
	v_mfma_f32_16x16x32_bf16 v[8:11], v[140:143], v[204:207], v[8:11]
	v_mfma_f32_16x16x32_bf16 v[52:55], v[144:147], v[172:175], v[52:55]
	v_mfma_f32_16x16x32_bf16 v[48:51], v[152:155], v[172:175], v[48:51]
	v_mfma_f32_16x16x32_bf16 v[36:39], v[144:147], v[184:187], v[36:39]
	v_mfma_f32_16x16x32_bf16 v[32:35], v[152:155], v[184:187], v[32:35]
	v_mfma_f32_16x16x32_bf16 v[20:23], v[144:147], v[192:195], v[20:23]
	v_mfma_f32_16x16x32_bf16 v[16:19], v[152:155], v[192:195], v[16:19]
	v_mfma_f32_16x16x32_bf16 v[4:7], v[144:147], v[200:203], v[4:7]
	v_mfma_f32_16x16x32_bf16 v[0:3], v[152:155], v[200:203], v[0:3]
	v_mfma_f32_16x16x32_bf16 v[52:55], v[148:151], v[180:183], v[52:55]
	v_mfma_f32_16x16x32_bf16 v[48:51], v[156:159], v[180:183], v[48:51]
	v_mfma_f32_16x16x32_bf16 v[36:39], v[148:151], v[188:191], v[36:39]
	v_mfma_f32_16x16x32_bf16 v[32:35], v[156:159], v[188:191], v[32:35]
	v_mfma_f32_16x16x32_bf16 v[20:23], v[148:151], v[196:199], v[20:23]
	v_mfma_f32_16x16x32_bf16 v[16:19], v[156:159], v[196:199], v[16:19]
	v_mfma_f32_16x16x32_bf16 v[4:7], v[148:151], v[204:207], v[4:7]
	v_mfma_f32_16x16x32_bf16 v[0:3], v[156:159], v[204:207], v[0:3]
	s_barrier
	s_add_u32 s10, s10, 0x100
	s_addc_u32 s11, s11, 0
	s_add_u32 s2, s2, 0x100
	s_addc_u32 s3, s3, 0
	s_cmp_ge_u32 s26, s51
	s_mov_b32 s8, s26
	s_cbranch_scc1 .Lkl_done

; #define PG8_BAR __builtin_amdgcn_s_barrier()
; template <class Epi, class Sched, bool ALIGN_EPI = false, bool SP2 = false>
; __device__ __forceinline__ void gemm_phase(PG8_LAS unsigned char* lds, const Gemm g, const Sched& S, const Epi& E) {
;     ...
;         }
;         if constexpr (ALIGN_EPI) { if (wr == 0) PG8_BAR; }
.Lkl_done:
	s_and_b64 vcc, exec, s[22:23]
	s_cbranch_vccz .LBB0_310
	s_barrier
